# attention tile bodies: additionally pack adjacent scalar f32 add/mul pairs of the row-sum and rescale code into v_pk_add_f32 / v_pk_mul_f32
# speedup vs baseline: 1.0012x; 1.0012x over previous
; DEVI unsigned pk_bf16(float lo, float hi) { unsigned r; asm("v_cvt_pk_bf16_f32 %0, %1, %2" : "=v"(r) : "v"(lo), "v"(hi)); return r; }
; DEVI bf16x8 mk8(uint2 a, uint2 b) { union { uint4 u; bf16x8 v; } c; c.u = make_uint4(a.x, a.y, b.x, b.y); return c.v; }
; template <int DK, bool BIAS> ...
;     ...
;       for (int qi = 0; qi < 2; ++qi) {
;         float mx = -3e38f;
;         if (BIAS) {
; #pragma unroll
;           for (int kt = 0; kt < 4; ++kt) { const f32x4 nf = *(const f32x4*)(fkm + buf * 64 + 16 * kt + 4 * fq);
; #pragma unroll
;             for (int r = 0; r < 4; ++r) { const float t = fmaf(S[kt][qi][r], sc2, nf[r]); S[kt][qi][r] = t; mx = fmaxf(mx, t); } }
;         } else {
; #pragma unroll
;           for (int kt = 0; kt < 4; ++kt)
; #pragma unroll
;             for (int r = 0; r < 4; ++r) mx = fmaxf(mx, S[kt][qi][r]);
;           mx *= sc2;
;         }
;         mx = fmaxf(mx, __shfl_xor(mx, 16)); mx = fmaxf(mx, __shfl_xor(mx, 32));
;         const float mold = mrun[qi], mnew = fmaxf(mold, mx);
;         mrun[qi] = mnew;
;         float ps = 0.f;
; #pragma unroll
;         for (int kt = 0; kt < 4; ++kt)
; #pragma unroll
;           for (int r = 0; r < 4; ++r) { const float pv = BIAS ? __builtin_amdgcn_exp2f(S[kt][qi][r] - mnew) : __builtin_amdgcn_exp2f(fmaf(S[kt][qi][r], sc2, -mnew)); S[kt][qi][r] = pv; ps += pv; }
;         {
;           const float alpha = __builtin_amdgcn_exp2f(mold - mnew);
;           lrun[qi] *= alpha;
; #pragma unroll
;           for (int et = 0; et < 4; ++et) O[et][qi] *= alpha;
;         }
;         lrun[qi] += ps;
; #pragma unroll
;         for (int k2 = 0; k2 < 2; ++k2) { uint2 lo, hi; lo.x = pk_bf16(S[2 * k2][qi][0], S[2 * k2][qi][1]); lo.y = pk_bf16(S[2 * k2][qi][2], S[2 * k2][qi][3]);
;           hi.x = pk_bf16(S[2 * k2 + 1][qi][0], S[2 * k2 + 1][qi][1]); hi.y = pk_bf16(S[2 * k2 + 1][qi][2], S[2 * k2 + 1][qi][3]); pf[qi][k2] = mk8(lo, hi); }
;       }
.LBB0_1776:
	s_or_b64 exec, exec, s[18:19]
	ds_read_b128 v[174:177], v168 offset:36864
	ds_read_b128 v[194:197], v168 offset:36928
	ds_read_b128 v[242:245], v168 offset:36992
	ds_read_b128 v[246:249], v168 offset:37056
	s_mov_b32 s100, 0x3e38aa3b
	s_mov_b32 s101, 0x3e38aa3b
	v_lshlrev_b32_e32 v250, 2, v186
	v_lshlrev_b32_e32 v251, 2, v185
	s_waitcnt lgkmcnt(3)
	v_pk_fma_f32 v[210:211], v[80:81], s[100:101], v[174:175]
	v_pk_fma_f32 v[212:213], v[82:83], s[100:101], v[176:177]
	v_pk_fma_f32 v[226:227], v[64:65], s[100:101], v[174:175]
	v_pk_fma_f32 v[228:229], v[66:67], s[100:101], v[176:177]
	s_waitcnt lgkmcnt(2)
	v_pk_fma_f32 v[214:215], v[86:87], s[100:101], v[194:195]
	v_pk_fma_f32 v[216:217], v[88:89], s[100:101], v[196:197]
	v_pk_fma_f32 v[230:231], v[68:69], s[100:101], v[194:195]
	v_pk_fma_f32 v[232:233], v[70:71], s[100:101], v[196:197]
	s_waitcnt lgkmcnt(1)
	v_pk_fma_f32 v[218:219], v[90:91], s[100:101], v[242:243]
	v_pk_fma_f32 v[220:221], v[92:93], s[100:101], v[244:245]
	v_pk_fma_f32 v[234:235], v[72:73], s[100:101], v[242:243]
	v_pk_fma_f32 v[236:237], v[74:75], s[100:101], v[244:245]
	s_waitcnt lgkmcnt(0)
	v_pk_fma_f32 v[222:223], v[94:95], s[100:101], v[246:247]
	v_pk_fma_f32 v[224:225], v[96:97], s[100:101], v[248:249]
	v_pk_fma_f32 v[238:239], v[76:77], s[100:101], v[246:247]
	v_pk_fma_f32 v[240:241], v[78:79], s[100:101], v[248:249]
	v_max3_f32 v84, v210, s31, v211
	v_max3_f32 v85, v226, s31, v227
	v_max3_f32 v84, v84, v212, v213
	v_max3_f32 v85, v85, v228, v229
	v_max3_f32 v84, v84, v214, v215
	v_max3_f32 v85, v85, v230, v231
	v_max3_f32 v84, v84, v216, v217
	v_max3_f32 v85, v85, v232, v233
	v_max3_f32 v84, v84, v218, v219
	v_max3_f32 v85, v85, v234, v235
	v_max3_f32 v84, v84, v220, v221
	v_max3_f32 v85, v85, v236, v237
	v_max3_f32 v84, v84, v222, v223
	v_max3_f32 v85, v85, v238, v239
	v_max3_f32 v84, v84, v224, v225
	v_max3_f32 v85, v85, v240, v241
	ds_bpermute_b32 v86, v250, v84
	ds_bpermute_b32 v87, v250, v85
	s_waitcnt lgkmcnt(0)
	v_max_f32_e32 v84, v84, v86
	v_max_f32_e32 v85, v85, v87
	ds_bpermute_b32 v86, v251, v84
	ds_bpermute_b32 v87, v251, v85
	s_waitcnt lgkmcnt(0)
	v_max3_f32 v131, v114, v84, v86
	v_max3_f32 v173, v112, v85, v87
	v_sub_f32_e32 v84, v114, v131
	v_sub_f32_e32 v85, v112, v173
	v_exp_f32_e32 v126, v84
	v_exp_f32_e32 v82, v85
	v_sub_f32_e32 v86, 0, v131
	v_sub_f32_e32 v80, 0, v173
	v_pk_add_f32 v[210:211], v[210:211], v[86:87] op_sel_hi:[1,0]
	v_pk_add_f32 v[212:213], v[212:213], v[86:87] op_sel_hi:[1,0]
	v_pk_add_f32 v[226:227], v[226:227], v[80:81] op_sel_hi:[1,0]
	v_pk_add_f32 v[228:229], v[228:229], v[80:81] op_sel_hi:[1,0]
	v_pk_add_f32 v[214:215], v[214:215], v[86:87] op_sel_hi:[1,0]
	v_pk_add_f32 v[216:217], v[216:217], v[86:87] op_sel_hi:[1,0]
	v_pk_add_f32 v[230:231], v[230:231], v[80:81] op_sel_hi:[1,0]
	v_pk_add_f32 v[232:233], v[232:233], v[80:81] op_sel_hi:[1,0]
	v_pk_add_f32 v[218:219], v[218:219], v[86:87] op_sel_hi:[1,0]
	v_pk_add_f32 v[220:221], v[220:221], v[86:87] op_sel_hi:[1,0]
	v_pk_add_f32 v[234:235], v[234:235], v[80:81] op_sel_hi:[1,0]
	v_pk_add_f32 v[236:237], v[236:237], v[80:81] op_sel_hi:[1,0]
	v_pk_add_f32 v[222:223], v[222:223], v[86:87] op_sel_hi:[1,0]
	v_pk_add_f32 v[224:225], v[224:225], v[86:87] op_sel_hi:[1,0]
	v_pk_add_f32 v[238:239], v[238:239], v[80:81] op_sel_hi:[1,0]
	v_pk_add_f32 v[240:241], v[240:241], v[80:81] op_sel_hi:[1,0]
	v_exp_f32_e32 v155, v210
	v_exp_f32_e32 v154, v226
	v_exp_f32_e32 v157, v211
	v_exp_f32_e32 v156, v227
	v_exp_f32_e32 v151, v212
	v_exp_f32_e32 v150, v228
	v_exp_f32_e32 v153, v213
	v_exp_f32_e32 v152, v229
	v_exp_f32_e32 v117, v214
	v_exp_f32_e32 v116, v230
	v_exp_f32_e32 v119, v215
	v_exp_f32_e32 v118, v231
	v_exp_f32_e32 v123, v216
	v_exp_f32_e32 v122, v232
	v_exp_f32_e32 v121, v217
	v_exp_f32_e32 v120, v233
	v_exp_f32_e32 v125, v218
	v_exp_f32_e32 v124, v234
	v_exp_f32_e32 v89, v219
	v_exp_f32_e32 v88, v235
	v_exp_f32_e32 v95, v220
	v_exp_f32_e32 v94, v236
	v_exp_f32_e32 v115, v221
	v_exp_f32_e32 v114, v237
	v_exp_f32_e32 v93, v222
	v_exp_f32_e32 v92, v238
	v_exp_f32_e32 v113, v223
	v_exp_f32_e32 v112, v239
	v_exp_f32_e32 v91, v224
	v_exp_f32_e32 v90, v240
	v_exp_f32_e32 v97, v225
	v_exp_f32_e32 v96, v241
	v_pk_mul_f32 v[202:203], v[52:53], v[126:127] op_sel_hi:[1,0]
	v_pk_mul_f32 v[52:53], v[56:57], v[126:127] op_sel_hi:[1,0]
	v_pk_mul_f32 v[198:199], v[48:49], v[126:127] op_sel_hi:[1,0]
	v_pk_mul_f32 v[48:49], v[60:61], v[126:127] op_sel_hi:[1,0]
	v_add_u32_e32 v174, 0x4800, v170
	v_add_u32_e32 v175, 0x5000, v170
	v_pk_mul_f32 v[200:201], v[50:51], v[126:127] op_sel_hi:[1,0]
	v_add_u32_e32 v176, 0x5800, v170
	v_pk_mul_f32 v[204:205], v[54:55], v[126:127] op_sel_hi:[1,0]
	v_pk_add_f32 v[64:65], v[154:155], 0 op_sel_hi:[1,0]
	v_pk_add_f32 v[80:81], v[156:157], v[64:65]
	ds_read2_b64 v[64:67], v174 offset1:4
	ds_read2_b64 v[72:75], v175 offset0:32 offset1:36
	v_pk_mul_f32 v[46:47], v[46:47], v[82:83] op_sel_hi:[1,0]
	v_pk_mul_f32 v[44:45], v[44:45], v[82:83] op_sel_hi:[1,0]
	v_pk_mul_f32 v[54:55], v[58:59], v[126:127] op_sel_hi:[1,0]
	v_cvt_pk_bf16_f32 v56, v155, v157
	v_cvt_pk_bf16_f32 v57, v151, v153
	v_cvt_pk_bf16_f32 v58, v117, v119
	v_cvt_pk_bf16_f32 v59, v123, v121
	v_cvt_pk_bf16_f32 v68, v154, v156
	s_waitcnt lgkmcnt(1)
; DEVI unsigned pk_bf16(float lo, float hi) { unsigned r; asm("v_cvt_pk_bf16_f32 %0, %1, %2" : "=v"(r) : "v"(lo), "v"(hi)); return r; }
; DEVI bf16x8 mk8(uint2 a, uint2 b) { union { uint4 u; bf16x8 v; } c; c.u = make_uint4(a.x, a.y, b.x, b.y); return c.v; }
; #define MFMA(a, b, c) __builtin_amdgcn_mfma_f32_16x16x32_bf16((a), (b), (c), 0, 0, 0)
; template <int DK, bool BIAS> ...
;     ...
;         {
;           const float alpha = __builtin_amdgcn_exp2f(mold - mnew);
;           lrun[qi] *= alpha;
; #pragma unroll
;           for (int et = 0; et < 4; ++et) O[et][qi] *= alpha;
;         }
;         lrun[qi] += ps;
; #pragma unroll
;         for (int k2 = 0; k2 < 2; ++k2) { uint2 lo, hi; lo.x = pk_bf16(S[2 * k2][qi][0], S[2 * k2][qi][1]); lo.y = pk_bf16(S[2 * k2][qi][2], S[2 * k2][qi][3]);
;           hi.x = pk_bf16(S[2 * k2 + 1][qi][0], S[2 * k2 + 1][qi][1]); hi.y = pk_bf16(S[2 * k2 + 1][qi][2], S[2 * k2 + 1][qi][3]); pf[qi][k2] = mk8(lo, hi); }
;       }
; #pragma unroll
;       for (int k2 = 0; k2 < 2; ++k2)
; #pragma unroll
;         for (int et = 0; et < 4; ++et) {
;           const uint2 v0 = *(const uint2*)(Vtm + (buf * 64 + 16 * et + fr) * 72 + 32 * k2 + 4 * fq), v1 = *(const uint2*)(Vtm + (buf * 64 + 16 * et + fr) * 72 + 32 * k2 + 16 + 4 * fq);
;           const bf16x8 va = mk8(v0, v1);
; #pragma unroll
;           for (int qi = 0; qi < 2; ++qi) O[et][qi] = MFMA(va, pf[qi][k2], O[et][qi]);
;         }
	v_mfma_f32_16x16x32_bf16 v[76:79], v[64:67], v[56:59], v[198:201]
	v_cvt_pk_bf16_f32 v69, v150, v152
	v_cvt_pk_bf16_f32 v70, v116, v118
	v_cvt_pk_bf16_f32 v71, v122, v120
	v_pk_mul_f32 v[42:43], v[42:43], v[82:83] op_sel_hi:[1,0]
	s_nop 0
	v_mfma_f32_16x16x32_bf16 v[44:47], v[64:67], v[68:71], v[44:47]
	ds_read2_b64 v[64:67], v176 offset0:64 offset1:68
	v_pk_mul_f32 v[40:41], v[40:41], v[82:83] op_sel_hi:[1,0]
	v_add_u32_e32 v177, 0x6000, v170
	s_waitcnt lgkmcnt(1)
	v_mfma_f32_16x16x32_bf16 v[84:87], v[72:75], v[56:59], v[202:205]
	v_pk_mul_f32 v[50:51], v[62:63], v[126:127] op_sel_hi:[1,0]
	v_mfma_f32_16x16x32_bf16 v[40:43], v[72:75], v[68:71], v[40:43]
	ds_read2_b64 v[72:75], v177 offset0:96 offset1:100
	v_pk_mul_f32 v[38:39], v[38:39], v[82:83] op_sel_hi:[1,0]
	v_pk_mul_f32 v[36:37], v[36:37], v[82:83] op_sel_hi:[1,0]
	s_waitcnt lgkmcnt(1)
	v_mfma_f32_16x16x32_bf16 v[154:157], v[64:67], v[56:59], v[52:55]
	v_pk_mul_f32 v[34:35], v[34:35], v[82:83] op_sel_hi:[1,0]
	v_pk_mul_f32 v[32:33], v[32:33], v[82:83] op_sel_hi:[1,0]
	v_cvt_pk_bf16_f32 v60, v125, v89
	v_mfma_f32_16x16x32_bf16 v[36:39], v[64:67], v[68:71], v[36:39]
	ds_read2_b64 v[52:55], v174 offset0:8 offset1:12
	s_waitcnt lgkmcnt(1)
	v_mfma_f32_16x16x32_bf16 v[64:67], v[72:75], v[56:59], v[48:51]
	ds_read2_b64 v[56:59], v175 offset0:40 offset1:44
	v_cvt_pk_bf16_f32 v61, v95, v115
	v_cvt_pk_bf16_f32 v62, v93, v113
	v_cvt_pk_bf16_f32 v63, v91, v97
	s_nop 0
	v_mfma_f32_16x16x32_bf16 v[32:35], v[72:75], v[68:71], v[32:35]
	v_cvt_pk_bf16_f32 v68, v124, v88
	v_cvt_pk_bf16_f32 v69, v94, v114
	s_waitcnt lgkmcnt(1)
	v_mfma_f32_16x16x32_bf16 v[48:51], v[52:55], v[60:63], v[76:79]
	v_cvt_pk_bf16_f32 v70, v92, v112
	v_cvt_pk_bf16_f32 v71, v90, v96
	ds_read2_b64 v[72:75], v176 offset0:72 offset1:76
	s_nop 0
	v_mfma_f32_16x16x32_bf16 v[44:47], v[52:55], v[68:71], v[44:47]
	v_pk_add_f32 v[52:53], v[150:151], v[80:81]
	v_mov_b32_e32 v83, v126
	v_pk_add_f32 v[76:77], v[152:153], v[52:53]
	s_waitcnt lgkmcnt(1)
	v_mfma_f32_16x16x32_bf16 v[52:55], v[56:59], v[60:63], v[84:87]
	v_pk_add_f32 v[76:77], v[116:117], v[76:77]
	v_pk_add_f32 v[76:77], v[118:119], v[76:77]
	v_mfma_f32_16x16x32_bf16 v[40:43], v[56:59], v[68:71], v[40:43]
	v_pk_add_f32 v[76:77], v[122:123], v[76:77]
	v_pk_add_f32 v[56:57], v[120:121], v[76:77]
	ds_read2_b64 v[76:79], v177 offset0:104 offset1:108
	v_pk_add_f32 v[80:81], v[124:125], v[56:57]
	s_waitcnt lgkmcnt(1)
	v_mfma_f32_16x16x32_bf16 v[56:59], v[72:75], v[60:63], v[154:157]
	v_pk_add_f32 v[80:81], v[88:89], v[80:81]
	v_pk_add_f32 v[80:81], v[94:95], v[80:81]
	v_mfma_f32_16x16x32_bf16 v[36:39], v[72:75], v[68:71], v[36:39]
	v_pk_add_f32 v[80:81], v[114:115], v[80:81]
	v_mov_b32_e32 v114, v131
	v_pk_add_f32 v[72:73], v[92:93], v[80:81]
	s_waitcnt lgkmcnt(0)
	v_mfma_f32_16x16x32_bf16 v[60:63], v[76:79], v[60:63], v[64:67]
	v_pk_add_f32 v[72:73], v[112:113], v[72:73]
	v_mov_b32_e32 v112, v173
	v_mfma_f32_16x16x32_bf16 v[32:35], v[76:79], v[68:71], v[32:35]
	v_pk_add_f32 v[64:65], v[90:91], v[72:73]
	v_pk_add_f32 v[64:65], v[96:97], v[64:65]
	s_nop 0
	v_pk_fma_f32 v[106:107], v[106:107], v[82:83], v[64:65]

; DEVI unsigned pk_bf16(float lo, float hi) { unsigned r; asm("v_cvt_pk_bf16_f32 %0, %1, %2" : "=v"(r) : "v"(lo), "v"(hi)); return r; }
; DEVI bf16x8 mk8(uint2 a, uint2 b) { union { uint4 u; bf16x8 v; } c; c.u = make_uint4(a.x, a.y, b.x, b.y); return c.v; }
; template <int DK, bool BIAS> ...
;     ...
;       for (int qi = 0; qi < 2; ++qi) {
;         float mx = -3e38f;
;         if (BIAS) {
; #pragma unroll
;           for (int kt = 0; kt < 4; ++kt) { const f32x4 nf = *(const f32x4*)(fkm + buf * 64 + 16 * kt + 4 * fq);
; #pragma unroll
;             for (int r = 0; r < 4; ++r) { const float t = fmaf(S[kt][qi][r], sc2, nf[r]); S[kt][qi][r] = t; mx = fmaxf(mx, t); } }
;         } else {
; #pragma unroll
;           for (int kt = 0; kt < 4; ++kt)
; #pragma unroll
;             for (int r = 0; r < 4; ++r) mx = fmaxf(mx, S[kt][qi][r]);
;           mx *= sc2;
;         }
;         mx = fmaxf(mx, __shfl_xor(mx, 16)); mx = fmaxf(mx, __shfl_xor(mx, 32));
;         const float mold = mrun[qi], mnew = fmaxf(mold, mx);
;         mrun[qi] = mnew;
;         float ps = 0.f;
; #pragma unroll
;         for (int kt = 0; kt < 4; ++kt)
; #pragma unroll
;           for (int r = 0; r < 4; ++r) { const float pv = BIAS ? __builtin_amdgcn_exp2f(S[kt][qi][r] - mnew) : __builtin_amdgcn_exp2f(fmaf(S[kt][qi][r], sc2, -mnew)); S[kt][qi][r] = pv; ps += pv; }
;         {
;           const float alpha = __builtin_amdgcn_exp2f(mold - mnew);
;           lrun[qi] *= alpha;
; #pragma unroll
;           for (int et = 0; et < 4; ++et) O[et][qi] *= alpha;
;         }
;         lrun[qi] += ps;
; #pragma unroll
;         for (int k2 = 0; k2 < 2; ++k2) { uint2 lo, hi; lo.x = pk_bf16(S[2 * k2][qi][0], S[2 * k2][qi][1]); lo.y = pk_bf16(S[2 * k2][qi][2], S[2 * k2][qi][3]);
;           hi.x = pk_bf16(S[2 * k2 + 1][qi][0], S[2 * k2 + 1][qi][1]); hi.y = pk_bf16(S[2 * k2 + 1][qi][2], S[2 * k2 + 1][qi][3]); pf[qi][k2] = mk8(lo, hi); }
;       }
.LBB0_1797:
	s_or_b64 exec, exec, s[18:19]
	ds_read_b128 v[174:177], v104 offset:37120
	ds_read_b128 v[194:197], v104 offset:37184
	ds_read_b128 v[242:245], v104 offset:37248
	ds_read_b128 v[246:249], v104 offset:37312
	s_mov_b32 s100, 0x3e38aa3b
	s_mov_b32 s101, 0x3e38aa3b
	v_lshlrev_b32_e32 v250, 2, v186
	v_lshlrev_b32_e32 v251, 2, v185
	s_waitcnt lgkmcnt(3)
	v_pk_fma_f32 v[210:211], v[80:81], s[100:101], v[174:175]
	v_pk_fma_f32 v[212:213], v[82:83], s[100:101], v[176:177]
	v_pk_fma_f32 v[226:227], v[64:65], s[100:101], v[174:175]
	v_pk_fma_f32 v[228:229], v[66:67], s[100:101], v[176:177]
	s_waitcnt lgkmcnt(2)
	v_pk_fma_f32 v[214:215], v[86:87], s[100:101], v[194:195]
	v_pk_fma_f32 v[216:217], v[88:89], s[100:101], v[196:197]
	v_pk_fma_f32 v[230:231], v[68:69], s[100:101], v[194:195]
	v_pk_fma_f32 v[232:233], v[70:71], s[100:101], v[196:197]
	s_waitcnt lgkmcnt(1)
	v_pk_fma_f32 v[218:219], v[90:91], s[100:101], v[242:243]
	v_pk_fma_f32 v[220:221], v[92:93], s[100:101], v[244:245]
	v_pk_fma_f32 v[234:235], v[72:73], s[100:101], v[242:243]
	v_pk_fma_f32 v[236:237], v[74:75], s[100:101], v[244:245]
	s_waitcnt lgkmcnt(0)
	v_pk_fma_f32 v[222:223], v[94:95], s[100:101], v[246:247]
	v_pk_fma_f32 v[224:225], v[96:97], s[100:101], v[248:249]
	v_pk_fma_f32 v[238:239], v[76:77], s[100:101], v[246:247]
	v_pk_fma_f32 v[240:241], v[78:79], s[100:101], v[248:249]
	v_max3_f32 v84, v210, s31, v211
	v_max3_f32 v85, v226, s31, v227
	v_max3_f32 v84, v84, v212, v213
	v_max3_f32 v85, v85, v228, v229
	v_max3_f32 v84, v84, v214, v215
	v_max3_f32 v85, v85, v230, v231
	v_max3_f32 v84, v84, v216, v217
	v_max3_f32 v85, v85, v232, v233
	v_max3_f32 v84, v84, v218, v219
	v_max3_f32 v85, v85, v234, v235
	v_max3_f32 v84, v84, v220, v221
	v_max3_f32 v85, v85, v236, v237
	v_max3_f32 v84, v84, v222, v223
	v_max3_f32 v85, v85, v238, v239
	v_max3_f32 v84, v84, v224, v225
	v_max3_f32 v85, v85, v240, v241
	ds_bpermute_b32 v86, v250, v84
	ds_bpermute_b32 v87, v250, v85
	s_waitcnt lgkmcnt(0)
	v_max_f32_e32 v84, v84, v86
	v_max_f32_e32 v85, v85, v87
	ds_bpermute_b32 v86, v251, v84
	ds_bpermute_b32 v87, v251, v85
	s_waitcnt lgkmcnt(0)
	v_max3_f32 v131, v114, v84, v86
	v_max3_f32 v173, v112, v85, v87
	v_sub_f32_e32 v84, v114, v131
	v_sub_f32_e32 v85, v112, v173
	v_exp_f32_e32 v126, v84
	v_exp_f32_e32 v82, v85
	v_sub_f32_e32 v86, 0, v131
	v_sub_f32_e32 v80, 0, v173
	v_pk_add_f32 v[210:211], v[210:211], v[86:87] op_sel_hi:[1,0]
	v_pk_add_f32 v[212:213], v[212:213], v[86:87] op_sel_hi:[1,0]
	v_pk_add_f32 v[226:227], v[226:227], v[80:81] op_sel_hi:[1,0]
	v_pk_add_f32 v[228:229], v[228:229], v[80:81] op_sel_hi:[1,0]
	v_pk_add_f32 v[214:215], v[214:215], v[86:87] op_sel_hi:[1,0]
	v_pk_add_f32 v[216:217], v[216:217], v[86:87] op_sel_hi:[1,0]
	v_pk_add_f32 v[230:231], v[230:231], v[80:81] op_sel_hi:[1,0]
	v_pk_add_f32 v[232:233], v[232:233], v[80:81] op_sel_hi:[1,0]
	v_pk_add_f32 v[218:219], v[218:219], v[86:87] op_sel_hi:[1,0]
	v_pk_add_f32 v[220:221], v[220:221], v[86:87] op_sel_hi:[1,0]
	v_pk_add_f32 v[234:235], v[234:235], v[80:81] op_sel_hi:[1,0]
	v_pk_add_f32 v[236:237], v[236:237], v[80:81] op_sel_hi:[1,0]
	v_pk_add_f32 v[222:223], v[222:223], v[86:87] op_sel_hi:[1,0]
	v_pk_add_f32 v[224:225], v[224:225], v[86:87] op_sel_hi:[1,0]
	v_pk_add_f32 v[238:239], v[238:239], v[80:81] op_sel_hi:[1,0]
	v_pk_add_f32 v[240:241], v[240:241], v[80:81] op_sel_hi:[1,0]
	v_exp_f32_e32 v155, v210
	v_exp_f32_e32 v154, v226
	v_exp_f32_e32 v157, v211
	v_exp_f32_e32 v156, v227
	v_exp_f32_e32 v151, v212
	v_exp_f32_e32 v150, v228
	v_exp_f32_e32 v153, v213
	v_exp_f32_e32 v152, v229
	v_exp_f32_e32 v117, v214
	v_exp_f32_e32 v116, v230
	v_exp_f32_e32 v119, v215
	v_exp_f32_e32 v118, v231
	v_exp_f32_e32 v123, v216
	v_exp_f32_e32 v122, v232
	v_exp_f32_e32 v121, v217
	v_exp_f32_e32 v120, v233
	v_exp_f32_e32 v125, v218
	v_exp_f32_e32 v124, v234
	v_exp_f32_e32 v89, v219
	v_exp_f32_e32 v88, v235
	v_exp_f32_e32 v95, v220
	v_exp_f32_e32 v94, v236
	v_exp_f32_e32 v115, v221
	v_exp_f32_e32 v114, v237
	v_exp_f32_e32 v93, v222
	v_exp_f32_e32 v92, v238
	v_exp_f32_e32 v113, v223
	v_exp_f32_e32 v112, v239
	v_exp_f32_e32 v91, v224
	v_exp_f32_e32 v90, v240
	v_exp_f32_e32 v97, v225
	v_exp_f32_e32 v96, v241
	v_pk_mul_f32 v[202:203], v[52:53], v[126:127] op_sel_hi:[1,0]
	v_pk_mul_f32 v[52:53], v[56:57], v[126:127] op_sel_hi:[1,0]
	v_pk_mul_f32 v[198:199], v[48:49], v[126:127] op_sel_hi:[1,0]
	v_pk_mul_f32 v[48:49], v[60:61], v[126:127] op_sel_hi:[1,0]
	v_add_u32_e32 v174, 0x6800, v170
	v_add_u32_e32 v175, 0x7000, v170
	v_pk_mul_f32 v[200:201], v[50:51], v[126:127] op_sel_hi:[1,0]
	v_add_u32_e32 v176, 0x7800, v170
	v_pk_mul_f32 v[204:205], v[54:55], v[126:127] op_sel_hi:[1,0]
	v_pk_add_f32 v[64:65], v[154:155], 0 op_sel_hi:[1,0]
	v_pk_add_f32 v[80:81], v[156:157], v[64:65]
	ds_read2_b64 v[64:67], v174 offset0:128 offset1:132
	ds_read2_b64 v[72:75], v175 offset0:160 offset1:164
	v_pk_mul_f32 v[46:47], v[46:47], v[82:83] op_sel_hi:[1,0]
	v_pk_mul_f32 v[44:45], v[44:45], v[82:83] op_sel_hi:[1,0]
	v_pk_mul_f32 v[54:55], v[58:59], v[126:127] op_sel_hi:[1,0]
	v_cvt_pk_bf16_f32 v56, v155, v157
	v_cvt_pk_bf16_f32 v57, v151, v153
	v_cvt_pk_bf16_f32 v58, v117, v119
	v_cvt_pk_bf16_f32 v59, v123, v121
	v_cvt_pk_bf16_f32 v68, v154, v156
	s_waitcnt lgkmcnt(1)
; DEVI unsigned pk_bf16(float lo, float hi) { unsigned r; asm("v_cvt_pk_bf16_f32 %0, %1, %2" : "=v"(r) : "v"(lo), "v"(hi)); return r; }
; DEVI bf16x8 mk8(uint2 a, uint2 b) { union { uint4 u; bf16x8 v; } c; c.u = make_uint4(a.x, a.y, b.x, b.y); return c.v; }
; #define MFMA(a, b, c) __builtin_amdgcn_mfma_f32_16x16x32_bf16((a), (b), (c), 0, 0, 0)
; template <int DK, bool BIAS> ...
;     ...
;         {
;           const float alpha = __builtin_amdgcn_exp2f(mold - mnew);
;           lrun[qi] *= alpha;
; #pragma unroll
;           for (int et = 0; et < 4; ++et) O[et][qi] *= alpha;
;         }
;         lrun[qi] += ps;
; #pragma unroll
;         for (int k2 = 0; k2 < 2; ++k2) { uint2 lo, hi; lo.x = pk_bf16(S[2 * k2][qi][0], S[2 * k2][qi][1]); lo.y = pk_bf16(S[2 * k2][qi][2], S[2 * k2][qi][3]);
;           hi.x = pk_bf16(S[2 * k2 + 1][qi][0], S[2 * k2 + 1][qi][1]); hi.y = pk_bf16(S[2 * k2 + 1][qi][2], S[2 * k2 + 1][qi][3]); pf[qi][k2] = mk8(lo, hi); }
;       }
; #pragma unroll
;       for (int k2 = 0; k2 < 2; ++k2)
; #pragma unroll
;         for (int et = 0; et < 4; ++et) {
;           const uint2 v0 = *(const uint2*)(Vtm + (buf * 64 + 16 * et + fr) * 72 + 32 * k2 + 4 * fq), v1 = *(const uint2*)(Vtm + (buf * 64 + 16 * et + fr) * 72 + 32 * k2 + 16 + 4 * fq);
;           const bf16x8 va = mk8(v0, v1);
; #pragma unroll
;           for (int qi = 0; qi < 2; ++qi) O[et][qi] = MFMA(va, pf[qi][k2], O[et][qi]);
;         }
	v_mfma_f32_16x16x32_bf16 v[76:79], v[64:67], v[56:59], v[198:201]
	v_cvt_pk_bf16_f32 v69, v150, v152
	v_cvt_pk_bf16_f32 v70, v116, v118
	v_cvt_pk_bf16_f32 v71, v122, v120
	v_pk_mul_f32 v[42:43], v[42:43], v[82:83] op_sel_hi:[1,0]
	s_nop 0
	v_mfma_f32_16x16x32_bf16 v[44:47], v[64:67], v[68:71], v[44:47]
	ds_read2_b64 v[64:67], v176 offset0:192 offset1:196
	v_pk_mul_f32 v[40:41], v[40:41], v[82:83] op_sel_hi:[1,0]
	v_add_u32_e32 v177, 0x8000, v170
	s_waitcnt lgkmcnt(1)
	v_mfma_f32_16x16x32_bf16 v[84:87], v[72:75], v[56:59], v[202:205]
	v_pk_mul_f32 v[50:51], v[62:63], v[126:127] op_sel_hi:[1,0]
	v_mfma_f32_16x16x32_bf16 v[40:43], v[72:75], v[68:71], v[40:43]
	ds_read2_b64 v[72:75], v177 offset0:224 offset1:228
	v_pk_mul_f32 v[38:39], v[38:39], v[82:83] op_sel_hi:[1,0]
	v_pk_mul_f32 v[36:37], v[36:37], v[82:83] op_sel_hi:[1,0]
	s_waitcnt lgkmcnt(1)
	v_mfma_f32_16x16x32_bf16 v[154:157], v[64:67], v[56:59], v[52:55]
	v_pk_mul_f32 v[34:35], v[34:35], v[82:83] op_sel_hi:[1,0]
	v_pk_mul_f32 v[32:33], v[32:33], v[82:83] op_sel_hi:[1,0]
	v_cvt_pk_bf16_f32 v60, v125, v89
	v_mfma_f32_16x16x32_bf16 v[36:39], v[64:67], v[68:71], v[36:39]
	ds_read2_b64 v[52:55], v174 offset0:136 offset1:140
	s_waitcnt lgkmcnt(1)
	v_mfma_f32_16x16x32_bf16 v[64:67], v[72:75], v[56:59], v[48:51]
	ds_read2_b64 v[56:59], v175 offset0:168 offset1:172
	v_cvt_pk_bf16_f32 v61, v95, v115
	v_cvt_pk_bf16_f32 v62, v93, v113
	v_cvt_pk_bf16_f32 v63, v91, v97
	s_nop 0
	v_mfma_f32_16x16x32_bf16 v[32:35], v[72:75], v[68:71], v[32:35]
	v_cvt_pk_bf16_f32 v68, v124, v88
	v_cvt_pk_bf16_f32 v69, v94, v114
	s_waitcnt lgkmcnt(1)
	v_mfma_f32_16x16x32_bf16 v[48:51], v[52:55], v[60:63], v[76:79]
	v_cvt_pk_bf16_f32 v70, v92, v112
	v_cvt_pk_bf16_f32 v71, v90, v96
	ds_read2_b64 v[72:75], v176 offset0:200 offset1:204
	s_nop 0
	v_mfma_f32_16x16x32_bf16 v[44:47], v[52:55], v[68:71], v[44:47]
	v_pk_add_f32 v[52:53], v[150:151], v[80:81]
	v_mov_b32_e32 v83, v126
	v_pk_add_f32 v[76:77], v[152:153], v[52:53]
	s_waitcnt lgkmcnt(1)
	v_mfma_f32_16x16x32_bf16 v[52:55], v[56:59], v[60:63], v[84:87]
	v_pk_add_f32 v[76:77], v[116:117], v[76:77]
	v_pk_add_f32 v[76:77], v[118:119], v[76:77]
	v_mfma_f32_16x16x32_bf16 v[40:43], v[56:59], v[68:71], v[40:43]
	v_pk_add_f32 v[76:77], v[122:123], v[76:77]
	v_pk_add_f32 v[56:57], v[120:121], v[76:77]
	ds_read2_b64 v[76:79], v177 offset0:232 offset1:236
	v_pk_add_f32 v[80:81], v[124:125], v[56:57]
	s_waitcnt lgkmcnt(1)
	v_mfma_f32_16x16x32_bf16 v[56:59], v[72:75], v[60:63], v[154:157]
	v_pk_add_f32 v[80:81], v[88:89], v[80:81]
	v_pk_add_f32 v[80:81], v[94:95], v[80:81]
	v_mfma_f32_16x16x32_bf16 v[36:39], v[72:75], v[68:71], v[36:39]
	v_pk_add_f32 v[80:81], v[114:115], v[80:81]
	v_mov_b32_e32 v114, v131
	v_pk_add_f32 v[72:73], v[92:93], v[80:81]
	s_waitcnt lgkmcnt(0)
	v_mfma_f32_16x16x32_bf16 v[60:63], v[76:79], v[60:63], v[64:67]
	v_pk_add_f32 v[72:73], v[112:113], v[72:73]
	v_mov_b32_e32 v112, v173
	v_mfma_f32_16x16x32_bf16 v[32:35], v[76:79], v[68:71], v[32:35]
	v_pk_add_f32 v[64:65], v[90:91], v[72:73]
	v_pk_add_f32 v[64:65], v[96:97], v[64:65]
	s_nop 0
	v_pk_fma_f32 v[106:107], v[106:107], v[82:83], v[64:65]

; DEVI unsigned pk_bf16(float lo, float hi) { unsigned r; asm("v_cvt_pk_bf16_f32 %0, %1, %2" : "=v"(r) : "v"(lo), "v"(hi)); return r; }
; DEVI bf16x8 mk8(uint2 a, uint2 b) { union { uint4 u; bf16x8 v; } c; c.u = make_uint4(a.x, a.y, b.x, b.y); return c.v; }
; template <int DK, bool BIAS> ...
;     ...
;       for (int qi = 0; qi < 2; ++qi) {
;         float mx = -3e38f;
;         if (BIAS) {
; #pragma unroll
;           for (int kt = 0; kt < 4; ++kt) { const f32x4 nf = *(const f32x4*)(fkm + buf * 64 + 16 * kt + 4 * fq);
; #pragma unroll
;             for (int r = 0; r < 4; ++r) { const float t = fmaf(S[kt][qi][r], sc2, nf[r]); S[kt][qi][r] = t; mx = fmaxf(mx, t); } }
;         } else {
; #pragma unroll
;           for (int kt = 0; kt < 4; ++kt)
; #pragma unroll
;             for (int r = 0; r < 4; ++r) mx = fmaxf(mx, S[kt][qi][r]);
;           mx *= sc2;
;         }
;         mx = fmaxf(mx, __shfl_xor(mx, 16)); mx = fmaxf(mx, __shfl_xor(mx, 32));
;         const float mold = mrun[qi], mnew = fmaxf(mold, mx);
;         mrun[qi] = mnew;
;         float ps = 0.f;
; #pragma unroll
;         for (int kt = 0; kt < 4; ++kt)
; #pragma unroll
;           for (int r = 0; r < 4; ++r) { const float pv = BIAS ? __builtin_amdgcn_exp2f(S[kt][qi][r] - mnew) : __builtin_amdgcn_exp2f(fmaf(S[kt][qi][r], sc2, -mnew)); S[kt][qi][r] = pv; ps += pv; }
;         {
;           const float alpha = __builtin_amdgcn_exp2f(mold - mnew);
;           lrun[qi] *= alpha;
; #pragma unroll
;           for (int et = 0; et < 4; ++et) O[et][qi] *= alpha;
;         }
;         lrun[qi] += ps;
; #pragma unroll
;         for (int k2 = 0; k2 < 2; ++k2) { uint2 lo, hi; lo.x = pk_bf16(S[2 * k2][qi][0], S[2 * k2][qi][1]); lo.y = pk_bf16(S[2 * k2][qi][2], S[2 * k2][qi][3]);
;           hi.x = pk_bf16(S[2 * k2 + 1][qi][0], S[2 * k2 + 1][qi][1]); hi.y = pk_bf16(S[2 * k2 + 1][qi][2], S[2 * k2 + 1][qi][3]); pf[qi][k2] = mk8(lo, hi); }
;       }
.LBB0_1866:
	s_or_b64 exec, exec, s[18:19]
	s_mov_b32 s100, s34
	s_mov_b32 s101, s34
	v_lshlrev_b32_e32 v250, 2, v186
	v_lshlrev_b32_e32 v251, 2, v185
	v_max3_f32 v242, v96, s31, v97
	v_max3_f32 v243, v84, s31, v85
	v_max3_f32 v242, v242, v98, v99
	v_max3_f32 v243, v243, v86, v87
	v_max3_f32 v242, v242, v100, v101
	v_max3_f32 v243, v243, v88, v89
	v_max3_f32 v242, v242, v102, v103
	v_max3_f32 v243, v243, v90, v91
	v_max3_f32 v242, v242, v104, v105
	v_max3_f32 v243, v243, v80, v81
	v_max3_f32 v242, v242, v106, v107
	v_max3_f32 v243, v243, v82, v83
	v_max3_f32 v242, v242, v108, v109
	v_max3_f32 v243, v243, v92, v93
	v_max3_f32 v242, v242, v110, v111
	v_max3_f32 v243, v243, v94, v95
	v_mul_f32_e32 v242, 0x3e16c740, v242
	v_mul_f32_e32 v243, 0x3e16c740, v243
	ds_bpermute_b32 v244, v250, v242
	ds_bpermute_b32 v245, v250, v243
	s_waitcnt lgkmcnt(0)
	v_max_f32_e32 v242, v242, v244
	v_max_f32_e32 v243, v243, v245
	ds_bpermute_b32 v244, v251, v242
	ds_bpermute_b32 v245, v251, v243
	s_waitcnt lgkmcnt(0)
	v_max3_f32 v131, v154, v242, v244
	v_max3_f32 v209, v208, v243, v245
	v_sub_f32_e32 v242, v154, v131
	v_sub_f32_e32 v243, v208, v209
	v_sub_f32_e32 v246, 0, v131
	v_sub_f32_e32 v248, 0, v209
	v_pk_fma_f32 v[210:211], v[96:97], s[100:101], v[246:247] op_sel_hi:[1,1,0]
	v_pk_fma_f32 v[226:227], v[80:81], s[100:101], v[248:249] op_sel_hi:[1,1,0]
	v_pk_fma_f32 v[212:213], v[98:99], s[100:101], v[246:247] op_sel_hi:[1,1,0]
	v_pk_fma_f32 v[228:229], v[82:83], s[100:101], v[248:249] op_sel_hi:[1,1,0]
	v_pk_fma_f32 v[214:215], v[100:101], s[100:101], v[246:247] op_sel_hi:[1,1,0]
	v_pk_fma_f32 v[230:231], v[84:85], s[100:101], v[248:249] op_sel_hi:[1,1,0]
	v_pk_fma_f32 v[216:217], v[102:103], s[100:101], v[246:247] op_sel_hi:[1,1,0]
	v_pk_fma_f32 v[232:233], v[86:87], s[100:101], v[248:249] op_sel_hi:[1,1,0]
	v_pk_fma_f32 v[218:219], v[104:105], s[100:101], v[246:247] op_sel_hi:[1,1,0]
	v_pk_fma_f32 v[234:235], v[88:89], s[100:101], v[248:249] op_sel_hi:[1,1,0]
	v_pk_fma_f32 v[220:221], v[106:107], s[100:101], v[246:247] op_sel_hi:[1,1,0]
	v_pk_fma_f32 v[236:237], v[90:91], s[100:101], v[248:249] op_sel_hi:[1,1,0]
	v_pk_fma_f32 v[222:223], v[108:109], s[100:101], v[246:247] op_sel_hi:[1,1,0]
	v_pk_fma_f32 v[238:239], v[92:93], s[100:101], v[248:249] op_sel_hi:[1,1,0]
	v_pk_fma_f32 v[224:225], v[110:111], s[100:101], v[246:247] op_sel_hi:[1,1,0]
	v_pk_fma_f32 v[240:241], v[94:95], s[100:101], v[248:249] op_sel_hi:[1,1,0]
	v_exp_f32_e32 v178, v242
	v_exp_f32_e32 v90, v243
	v_exp_f32_e32 v163, v210
	v_exp_f32_e32 v170, v226
	v_exp_f32_e32 v165, v211
	v_exp_f32_e32 v104, v227
	v_exp_f32_e32 v167, v212
	v_exp_f32_e32 v172, v228
	v_exp_f32_e32 v169, v213
	v_exp_f32_e32 v106, v229
	v_exp_f32_e32 v155, v214
	v_exp_f32_e32 v162, v230
	v_exp_f32_e32 v157, v215
	v_exp_f32_e32 v164, v231
	v_exp_f32_e32 v159, v216
	v_exp_f32_e32 v166, v232
	v_exp_f32_e32 v161, v217
	v_exp_f32_e32 v168, v233
	v_exp_f32_e32 v171, v218
	v_exp_f32_e32 v154, v234
	v_exp_f32_e32 v105, v219
	v_exp_f32_e32 v156, v235
	v_exp_f32_e32 v173, v220
	v_exp_f32_e32 v158, v236
	v_exp_f32_e32 v107, v221
	v_exp_f32_e32 v160, v237
	v_exp_f32_e32 v175, v222
	v_exp_f32_e32 v174, v238
	v_exp_f32_e32 v109, v223
	v_exp_f32_e32 v108, v239
	v_exp_f32_e32 v177, v224
	v_exp_f32_e32 v176, v240
	v_exp_f32_e32 v111, v225
	v_exp_f32_e32 v110, v241
	v_pk_add_f32 v[80:81], v[154:155], 0 op_sel_hi:[1,0]
	v_pk_add_f32 v[80:81], v[156:157], v[80:81]
	v_pk_add_f32 v[80:81], v[158:159], v[80:81]
	v_pk_add_f32 v[80:81], v[160:161], v[80:81]
	v_pk_add_f32 v[80:81], v[162:163], v[80:81]
	v_pk_mul_f32 v[102:103], v[66:67], v[178:179] op_sel_hi:[1,0]
	v_pk_add_f32 v[80:81], v[164:165], v[80:81]
	v_pk_mul_f32 v[100:101], v[64:65], v[178:179] op_sel_hi:[1,0]
	v_pk_add_f32 v[80:81], v[166:167], v[80:81]
	v_pk_mul_f32 v[64:65], v[76:77], v[178:179] op_sel_hi:[1,0]
	v_pk_add_f32 v[80:81], v[168:169], v[80:81]
	v_cvt_pk_bf16_f32 v76, v171, v105
	v_pk_mul_f32 v[98:99], v[70:71], v[178:179] op_sel_hi:[1,0]
	v_pk_add_f32 v[80:81], v[170:171], v[80:81]
	v_pk_mul_f32 v[96:97], v[68:69], v[178:179] op_sel_hi:[1,0]
	v_pk_add_f32 v[88:89], v[104:105], v[80:81]
	v_add_u32_e32 v105, 0x7000, v203
	v_cvt_pk_bf16_f32 v68, v155, v157
	v_cvt_pk_bf16_f32 v69, v159, v161
	v_pk_mul_f32 v[84:85], v[52:53], v[90:91] op_sel_hi:[1,0]
	v_pk_add_f32 v[52:53], v[172:173], v[88:89]
	v_pk_mul_f32 v[82:83], v[50:51], v[90:91] op_sel_hi:[1,0]
	v_pk_add_f32 v[52:53], v[106:107], v[52:53]
	v_pk_mul_f32 v[80:81], v[48:49], v[90:91] op_sel_hi:[1,0]
	v_pk_add_f32 v[52:53], v[174:175], v[52:53]
	v_pk_mul_f32 v[86:87], v[54:55], v[90:91] op_sel_hi:[1,0]
	v_pk_add_f32 v[52:53], v[108:109], v[52:53]
	v_pk_mul_f32 v[58:59], v[58:59], v[90:91] op_sel_hi:[1,0]
	v_pk_add_f32 v[52:53], v[176:177], v[52:53]
	v_pk_mul_f32 v[56:57], v[56:57], v[90:91] op_sel_hi:[1,0]
	v_pk_mul_f32 v[50:51], v[62:63], v[90:91] op_sel_hi:[1,0]
	v_pk_mul_f32 v[48:49], v[60:61], v[90:91] op_sel_hi:[1,0]
	v_mov_b32_e32 v91, v178
	v_pk_add_f32 v[52:53], v[110:111], v[52:53]
	v_cvt_pk_bf16_f32 v60, v170, v104
	v_add_u32_e32 v104, 0x6800, v203
	v_pk_fma_f32 v[120:121], v[120:121], v[90:91], v[52:53]
	ds_read2_b64 v[88:91], v104 offset1:4
	v_cvt_pk_bf16_f32 v70, v163, v165
	v_cvt_pk_bf16_f32 v71, v167, v169
	v_cvt_pk_bf16_f32 v52, v154, v156
	v_cvt_pk_bf16_f32 v53, v158, v160
	v_cvt_pk_bf16_f32 v54, v162, v164
	v_cvt_pk_bf16_f32 v55, v166, v168
	v_cvt_pk_bf16_f32 v61, v172, v106
	s_waitcnt lgkmcnt(0)
; DEVI unsigned pk_bf16(float lo, float hi) { unsigned r; asm("v_cvt_pk_bf16_f32 %0, %1, %2" : "=v"(r) : "v"(lo), "v"(hi)); return r; }
; DEVI bf16x8 mk8(uint2 a, uint2 b) { union { uint4 u; bf16x8 v; } c; c.u = make_uint4(a.x, a.y, b.x, b.y); return c.v; }
; #define MFMA(a, b, c) __builtin_amdgcn_mfma_f32_16x16x32_bf16((a), (b), (c), 0, 0, 0)
; template <int DK, bool BIAS> ...
;     ...
;         {
;           const float alpha = __builtin_amdgcn_exp2f(mold - mnew);
;           lrun[qi] *= alpha;
; #pragma unroll
;           for (int et = 0; et < 4; ++et) O[et][qi] *= alpha;
;         }
;         lrun[qi] += ps;
; #pragma unroll
;         for (int k2 = 0; k2 < 2; ++k2) { uint2 lo, hi; lo.x = pk_bf16(S[2 * k2][qi][0], S[2 * k2][qi][1]); lo.y = pk_bf16(S[2 * k2][qi][2], S[2 * k2][qi][3]);
;           hi.x = pk_bf16(S[2 * k2 + 1][qi][0], S[2 * k2 + 1][qi][1]); hi.y = pk_bf16(S[2 * k2 + 1][qi][2], S[2 * k2 + 1][qi][3]); pf[qi][k2] = mk8(lo, hi); }
;       }
; #pragma unroll
;       for (int k2 = 0; k2 < 2; ++k2)
; #pragma unroll
;         for (int et = 0; et < 4; ++et) {
;           const uint2 v0 = *(const uint2*)(Vtm + (buf * 64 + 16 * et + fr) * 72 + 32 * k2 + 4 * fq), v1 = *(const uint2*)(Vtm + (buf * 64 + 16 * et + fr) * 72 + 32 * k2 + 16 + 4 * fq);
;           const bf16x8 va = mk8(v0, v1);
; #pragma unroll
;           for (int qi = 0; qi < 2; ++qi) O[et][qi] = MFMA(va, pf[qi][k2], O[et][qi]);
;         }
	v_mfma_f32_16x16x32_bf16 v[92:95], v[88:91], v[68:71], v[100:103]
	v_add_u32_e32 v106, 0x7800, v203
	v_pk_mul_f32 v[74:75], v[74:75], v[178:179] op_sel_hi:[1,0]
	v_pk_mul_f32 v[72:73], v[72:73], v[178:179] op_sel_hi:[1,0]
	v_mfma_f32_16x16x32_bf16 v[80:83], v[88:91], v[52:55], v[80:83]
	ds_read2_b64 v[88:91], v105 offset0:32 offset1:36
	v_cvt_pk_bf16_f32 v77, v173, v107
	v_add_u32_e32 v107, 0x8000, v203
	s_waitcnt lgkmcnt(0)
	v_mfma_f32_16x16x32_bf16 v[96:99], v[88:91], v[68:71], v[96:99]
	v_pk_mul_f32 v[66:67], v[78:79], v[178:179] op_sel_hi:[1,0]
	v_cvt_pk_bf16_f32 v78, v175, v109
	v_cvt_pk_bf16_f32 v79, v177, v111
	v_mfma_f32_16x16x32_bf16 v[84:87], v[88:91], v[52:55], v[84:87]
	ds_read2_b64 v[88:91], v106 offset0:64 offset1:68
	v_cvt_pk_bf16_f32 v62, v174, v108
	v_cvt_pk_bf16_f32 v63, v176, v110
	s_waitcnt lgkmcnt(0)
	v_mfma_f32_16x16x32_bf16 v[72:75], v[88:91], v[68:71], v[72:75]
	v_mov_b32_e32 v208, v209
	v_mov_b32_e32 v154, v131
	v_mfma_f32_16x16x32_bf16 v[56:59], v[88:91], v[52:55], v[56:59]
	ds_read2_b64 v[88:91], v107 offset0:96 offset1:100
	s_waitcnt lgkmcnt(0)
	v_mfma_f32_16x16x32_bf16 v[100:103], v[88:91], v[68:71], v[64:67]
	v_mfma_f32_16x16x32_bf16 v[88:91], v[88:91], v[52:55], v[48:51]
	ds_read2_b64 v[52:55], v105 offset0:40 offset1:44
	s_nop 1
	ds_read2_b64 v[48:51], v104 offset0:8 offset1:12
	s_waitcnt lgkmcnt(0)
	v_mfma_f32_16x16x32_bf16 v[64:67], v[48:51], v[76:79], v[92:95]
	v_mfma_f32_16x16x32_bf16 v[48:51], v[48:51], v[60:63], v[80:83]
	s_nop 2
	ds_read2_b64 v[80:83], v106 offset0:72 offset1:76
	s_waitcnt lgkmcnt(0)
	v_mfma_f32_16x16x32_bf16 v[72:75], v[80:83], v[76:79], v[72:75]
	v_mfma_f32_16x16x32_bf16 v[56:59], v[80:83], v[60:63], v[56:59]
	ds_read2_b64 v[80:83], v107 offset0:104 offset1:108
	v_mfma_f32_16x16x32_bf16 v[68:71], v[52:55], v[76:79], v[96:99]
	v_mfma_f32_16x16x32_bf16 v[52:55], v[52:55], v[60:63], v[84:87]
	s_waitcnt lgkmcnt(0)
	v_mfma_f32_16x16x32_bf16 v[76:79], v[80:83], v[76:79], v[100:103]
	v_mfma_f32_16x16x32_bf16 v[60:63], v[80:83], v[60:63], v[88:91]

; DEVI unsigned pk_bf16(float lo, float hi) { unsigned r; asm("v_cvt_pk_bf16_f32 %0, %1, %2" : "=v"(r) : "v"(lo), "v"(hi)); return r; }
; DEVI bf16x8 mk8(uint2 a, uint2 b) { union { uint4 u; bf16x8 v; } c; c.u = make_uint4(a.x, a.y, b.x, b.y); return c.v; }
; template <int DK, bool BIAS> ...
;     ...
;       for (int qi = 0; qi < 2; ++qi) {
;         float mx = -3e38f;
;         if (BIAS) {
; #pragma unroll
;           for (int kt = 0; kt < 4; ++kt) { const f32x4 nf = *(const f32x4*)(fkm + buf * 64 + 16 * kt + 4 * fq);
; #pragma unroll
;             for (int r = 0; r < 4; ++r) { const float t = fmaf(S[kt][qi][r], sc2, nf[r]); S[kt][qi][r] = t; mx = fmaxf(mx, t); } }
;         } else {
; #pragma unroll
;           for (int kt = 0; kt < 4; ++kt)
; #pragma unroll
;             for (int r = 0; r < 4; ++r) mx = fmaxf(mx, S[kt][qi][r]);
;           mx *= sc2;
;         }
;         mx = fmaxf(mx, __shfl_xor(mx, 16)); mx = fmaxf(mx, __shfl_xor(mx, 32));
;         const float mold = mrun[qi], mnew = fmaxf(mold, mx);
;         mrun[qi] = mnew;
;         float ps = 0.f;
; #pragma unroll
;         for (int kt = 0; kt < 4; ++kt)
; #pragma unroll
;           for (int r = 0; r < 4; ++r) { const float pv = BIAS ? __builtin_amdgcn_exp2f(S[kt][qi][r] - mnew) : __builtin_amdgcn_exp2f(fmaf(S[kt][qi][r], sc2, -mnew)); S[kt][qi][r] = pv; ps += pv; }
;         {
;           const float alpha = __builtin_amdgcn_exp2f(mold - mnew);
;           lrun[qi] *= alpha;
; #pragma unroll
;           for (int et = 0; et < 4; ++et) O[et][qi] *= alpha;
;         }
;         lrun[qi] += ps;
; #pragma unroll
;         for (int k2 = 0; k2 < 2; ++k2) { uint2 lo, hi; lo.x = pk_bf16(S[2 * k2][qi][0], S[2 * k2][qi][1]); lo.y = pk_bf16(S[2 * k2][qi][2], S[2 * k2][qi][3]);
;           hi.x = pk_bf16(S[2 * k2 + 1][qi][0], S[2 * k2 + 1][qi][1]); hi.y = pk_bf16(S[2 * k2 + 1][qi][2], S[2 * k2 + 1][qi][3]); pf[qi][k2] = mk8(lo, hi); }
;       }
.LBB0_1888:
	s_or_b64 exec, exec, s[18:19]
	s_mov_b32 s100, s34
	s_mov_b32 s101, s34
	v_lshlrev_b32_e32 v250, 2, v186
	v_lshlrev_b32_e32 v251, 2, v185
	v_max3_f32 v242, v96, s31, v97
	v_max3_f32 v243, v84, s31, v85
	v_max3_f32 v242, v242, v98, v99
	v_max3_f32 v243, v243, v86, v87
	v_max3_f32 v242, v242, v100, v101
	v_max3_f32 v243, v243, v88, v89
	v_max3_f32 v242, v242, v102, v103
	v_max3_f32 v243, v243, v90, v91
	v_max3_f32 v242, v242, v104, v105
	v_max3_f32 v243, v243, v80, v81
	v_max3_f32 v242, v242, v106, v107
	v_max3_f32 v243, v243, v82, v83
	v_max3_f32 v242, v242, v108, v109
	v_max3_f32 v243, v243, v92, v93
	v_max3_f32 v242, v242, v110, v111
	v_max3_f32 v243, v243, v94, v95
	v_mul_f32_e32 v242, 0x3e16c740, v242
	v_mul_f32_e32 v243, 0x3e16c740, v243
	ds_bpermute_b32 v244, v250, v242
	ds_bpermute_b32 v245, v250, v243
	s_waitcnt lgkmcnt(0)
	v_max_f32_e32 v242, v242, v244
	v_max_f32_e32 v243, v243, v245
	ds_bpermute_b32 v244, v251, v242
	ds_bpermute_b32 v245, v251, v243
	s_waitcnt lgkmcnt(0)
	v_max3_f32 v131, v154, v242, v244
	v_max3_f32 v209, v208, v243, v245
	v_sub_f32_e32 v242, v154, v131
	v_sub_f32_e32 v243, v208, v209
	v_sub_f32_e32 v246, 0, v131
	v_sub_f32_e32 v248, 0, v209
	v_pk_fma_f32 v[210:211], v[96:97], s[100:101], v[246:247] op_sel_hi:[1,1,0]
	v_pk_fma_f32 v[226:227], v[80:81], s[100:101], v[248:249] op_sel_hi:[1,1,0]
	v_pk_fma_f32 v[212:213], v[98:99], s[100:101], v[246:247] op_sel_hi:[1,1,0]
	v_pk_fma_f32 v[228:229], v[82:83], s[100:101], v[248:249] op_sel_hi:[1,1,0]
	v_pk_fma_f32 v[214:215], v[100:101], s[100:101], v[246:247] op_sel_hi:[1,1,0]
	v_pk_fma_f32 v[230:231], v[84:85], s[100:101], v[248:249] op_sel_hi:[1,1,0]
	v_pk_fma_f32 v[216:217], v[102:103], s[100:101], v[246:247] op_sel_hi:[1,1,0]
	v_pk_fma_f32 v[232:233], v[86:87], s[100:101], v[248:249] op_sel_hi:[1,1,0]
	v_pk_fma_f32 v[218:219], v[104:105], s[100:101], v[246:247] op_sel_hi:[1,1,0]
	v_pk_fma_f32 v[234:235], v[88:89], s[100:101], v[248:249] op_sel_hi:[1,1,0]
	v_pk_fma_f32 v[220:221], v[106:107], s[100:101], v[246:247] op_sel_hi:[1,1,0]
	v_pk_fma_f32 v[236:237], v[90:91], s[100:101], v[248:249] op_sel_hi:[1,1,0]
	v_pk_fma_f32 v[222:223], v[108:109], s[100:101], v[246:247] op_sel_hi:[1,1,0]
	v_pk_fma_f32 v[238:239], v[92:93], s[100:101], v[248:249] op_sel_hi:[1,1,0]
	v_pk_fma_f32 v[224:225], v[110:111], s[100:101], v[246:247] op_sel_hi:[1,1,0]
	v_pk_fma_f32 v[240:241], v[94:95], s[100:101], v[248:249] op_sel_hi:[1,1,0]
	v_exp_f32_e32 v178, v242
	v_exp_f32_e32 v90, v243
	v_exp_f32_e32 v163, v210
	v_exp_f32_e32 v162, v226
	v_exp_f32_e32 v165, v211
	v_exp_f32_e32 v164, v227
	v_exp_f32_e32 v167, v212
	v_exp_f32_e32 v166, v228
	v_exp_f32_e32 v169, v213
	v_exp_f32_e32 v168, v229
	v_exp_f32_e32 v155, v214
	v_exp_f32_e32 v170, v230
	v_exp_f32_e32 v157, v215
	v_exp_f32_e32 v104, v231
	v_exp_f32_e32 v159, v216
	v_exp_f32_e32 v172, v232
	v_exp_f32_e32 v161, v217
	v_exp_f32_e32 v106, v233
	v_exp_f32_e32 v171, v218
	v_exp_f32_e32 v154, v234
	v_exp_f32_e32 v105, v219
	v_exp_f32_e32 v156, v235
	v_exp_f32_e32 v173, v220
	v_exp_f32_e32 v158, v236
	v_exp_f32_e32 v107, v221
	v_exp_f32_e32 v160, v237
	v_exp_f32_e32 v175, v222
	v_exp_f32_e32 v174, v238
	v_exp_f32_e32 v109, v223
	v_exp_f32_e32 v108, v239
	v_exp_f32_e32 v177, v224
	v_exp_f32_e32 v176, v240
	v_exp_f32_e32 v111, v225
	v_exp_f32_e32 v110, v241
	v_pk_add_f32 v[80:81], v[154:155], 0 op_sel_hi:[1,0]
	v_pk_add_f32 v[80:81], v[156:157], v[80:81]
	v_pk_mul_f32 v[102:103], v[66:67], v[178:179] op_sel_hi:[1,0]
	v_pk_add_f32 v[80:81], v[158:159], v[80:81]
	v_pk_mul_f32 v[100:101], v[64:65], v[178:179] op_sel_hi:[1,0]
	v_pk_add_f32 v[80:81], v[160:161], v[80:81]
	v_pk_mul_f32 v[64:65], v[76:77], v[178:179] op_sel_hi:[1,0]
	v_pk_add_f32 v[80:81], v[162:163], v[80:81]
	v_cvt_pk_bf16_f32 v76, v171, v105
	v_pk_mul_f32 v[98:99], v[70:71], v[178:179] op_sel_hi:[1,0]
	v_pk_add_f32 v[80:81], v[164:165], v[80:81]
	v_pk_mul_f32 v[96:97], v[68:69], v[178:179] op_sel_hi:[1,0]
	v_pk_add_f32 v[88:89], v[166:167], v[80:81]
	v_cvt_pk_bf16_f32 v68, v155, v157
	v_cvt_pk_bf16_f32 v69, v159, v161
	v_cvt_pk_bf16_f32 v70, v163, v165
	v_cvt_pk_bf16_f32 v71, v167, v169
	v_pk_mul_f32 v[74:75], v[74:75], v[178:179] op_sel_hi:[1,0]
	v_pk_mul_f32 v[84:85], v[52:53], v[90:91] op_sel_hi:[1,0]
	v_pk_add_f32 v[52:53], v[168:169], v[88:89]
	v_pk_mul_f32 v[82:83], v[50:51], v[90:91] op_sel_hi:[1,0]
	v_pk_add_f32 v[52:53], v[170:171], v[52:53]
	v_pk_mul_f32 v[80:81], v[48:49], v[90:91] op_sel_hi:[1,0]
	v_pk_add_f32 v[52:53], v[104:105], v[52:53]
	v_pk_mul_f32 v[86:87], v[54:55], v[90:91] op_sel_hi:[1,0]
	v_pk_add_f32 v[52:53], v[172:173], v[52:53]
	v_pk_mul_f32 v[58:59], v[58:59], v[90:91] op_sel_hi:[1,0]
	v_pk_add_f32 v[52:53], v[106:107], v[52:53]
	v_pk_mul_f32 v[56:57], v[56:57], v[90:91] op_sel_hi:[1,0]
	v_pk_add_f32 v[52:53], v[174:175], v[52:53]
	v_pk_mul_f32 v[50:51], v[62:63], v[90:91] op_sel_hi:[1,0]
	v_pk_add_f32 v[52:53], v[108:109], v[52:53]
	v_pk_mul_f32 v[48:49], v[60:61], v[90:91] op_sel_hi:[1,0]
	v_pk_add_f32 v[52:53], v[176:177], v[52:53]
	v_mov_b32_e32 v91, v178
	v_pk_add_f32 v[52:53], v[110:111], v[52:53]
	v_cvt_pk_bf16_f32 v60, v170, v104
	v_add_u32_e32 v104, 0x6800, v206
	v_pk_fma_f32 v[120:121], v[120:121], v[90:91], v[52:53]
	ds_read2_b64 v[88:91], v104 offset1:4
	v_add_u32_e32 v105, 0x9000, v203
	v_cvt_pk_bf16_f32 v52, v154, v156
	v_cvt_pk_bf16_f32 v53, v158, v160
	v_cvt_pk_bf16_f32 v54, v162, v164
	v_cvt_pk_bf16_f32 v55, v166, v168
	s_waitcnt lgkmcnt(0)
; DEVI unsigned pk_bf16(float lo, float hi) { unsigned r; asm("v_cvt_pk_bf16_f32 %0, %1, %2" : "=v"(r) : "v"(lo), "v"(hi)); return r; }
; DEVI bf16x8 mk8(uint2 a, uint2 b) { union { uint4 u; bf16x8 v; } c; c.u = make_uint4(a.x, a.y, b.x, b.y); return c.v; }
; #define MFMA(a, b, c) __builtin_amdgcn_mfma_f32_16x16x32_bf16((a), (b), (c), 0, 0, 0)
; template <int DK, bool BIAS> ...
;     ...
;         {
;           const float alpha = __builtin_amdgcn_exp2f(mold - mnew);
;           lrun[qi] *= alpha;
; #pragma unroll
;           for (int et = 0; et < 4; ++et) O[et][qi] *= alpha;
;         }
;         lrun[qi] += ps;
; #pragma unroll
;         for (int k2 = 0; k2 < 2; ++k2) { uint2 lo, hi; lo.x = pk_bf16(S[2 * k2][qi][0], S[2 * k2][qi][1]); lo.y = pk_bf16(S[2 * k2][qi][2], S[2 * k2][qi][3]);
;           hi.x = pk_bf16(S[2 * k2 + 1][qi][0], S[2 * k2 + 1][qi][1]); hi.y = pk_bf16(S[2 * k2 + 1][qi][2], S[2 * k2 + 1][qi][3]); pf[qi][k2] = mk8(lo, hi); }
;       }
; #pragma unroll
;       for (int k2 = 0; k2 < 2; ++k2)
; #pragma unroll
;         for (int et = 0; et < 4; ++et) {
;           const uint2 v0 = *(const uint2*)(Vtm + (buf * 64 + 16 * et + fr) * 72 + 32 * k2 + 4 * fq), v1 = *(const uint2*)(Vtm + (buf * 64 + 16 * et + fr) * 72 + 32 * k2 + 16 + 4 * fq);
;           const bf16x8 va = mk8(v0, v1);
; #pragma unroll
;           for (int qi = 0; qi < 2; ++qi) O[et][qi] = MFMA(va, pf[qi][k2], O[et][qi]);
;         }
	v_mfma_f32_16x16x32_bf16 v[92:95], v[88:91], v[68:71], v[100:103]
	v_cvt_pk_bf16_f32 v61, v172, v106
	v_add_u32_e32 v106, 0x9800, v203
	v_pk_mul_f32 v[72:73], v[72:73], v[178:179] op_sel_hi:[1,0]
	v_mfma_f32_16x16x32_bf16 v[80:83], v[88:91], v[52:55], v[80:83]
	ds_read2_b64 v[88:91], v105 offset0:160 offset1:164
	v_cvt_pk_bf16_f32 v77, v173, v107
	v_add_u32_e32 v107, 0xa000, v203
	s_waitcnt lgkmcnt(0)
	v_mfma_f32_16x16x32_bf16 v[96:99], v[88:91], v[68:71], v[96:99]
	v_pk_mul_f32 v[66:67], v[78:79], v[178:179] op_sel_hi:[1,0]
	v_cvt_pk_bf16_f32 v78, v175, v109
	v_cvt_pk_bf16_f32 v79, v177, v111
	v_mfma_f32_16x16x32_bf16 v[84:87], v[88:91], v[52:55], v[84:87]
	ds_read2_b64 v[88:91], v106 offset0:192 offset1:196
	v_cvt_pk_bf16_f32 v62, v174, v108
	v_cvt_pk_bf16_f32 v63, v176, v110
	s_waitcnt lgkmcnt(0)
	v_mfma_f32_16x16x32_bf16 v[72:75], v[88:91], v[68:71], v[72:75]
	v_mov_b32_e32 v208, v209
	v_mov_b32_e32 v154, v131
	v_mfma_f32_16x16x32_bf16 v[56:59], v[88:91], v[52:55], v[56:59]
	ds_read2_b64 v[88:91], v107 offset0:224 offset1:228
	s_waitcnt lgkmcnt(0)
	v_mfma_f32_16x16x32_bf16 v[100:103], v[88:91], v[68:71], v[64:67]
	v_mfma_f32_16x16x32_bf16 v[88:91], v[88:91], v[52:55], v[48:51]
	ds_read2_b64 v[52:55], v105 offset0:168 offset1:172
	s_nop 1
	ds_read2_b64 v[48:51], v104 offset0:8 offset1:12
	s_waitcnt lgkmcnt(0)
	v_mfma_f32_16x16x32_bf16 v[64:67], v[48:51], v[76:79], v[92:95]
	v_mfma_f32_16x16x32_bf16 v[48:51], v[48:51], v[60:63], v[80:83]
	s_nop 2
	ds_read2_b64 v[80:83], v106 offset0:200 offset1:204
	s_waitcnt lgkmcnt(0)
	v_mfma_f32_16x16x32_bf16 v[72:75], v[80:83], v[76:79], v[72:75]
	v_mfma_f32_16x16x32_bf16 v[56:59], v[80:83], v[60:63], v[56:59]
	ds_read2_b64 v[80:83], v107 offset0:232 offset1:236
	v_mfma_f32_16x16x32_bf16 v[68:71], v[52:55], v[76:79], v[96:99]
	v_mfma_f32_16x16x32_bf16 v[52:55], v[52:55], v[60:63], v[84:87]
	s_waitcnt lgkmcnt(0)
	v_mfma_f32_16x16x32_bf16 v[76:79], v[80:83], v[76:79], v[100:103]
	v_mfma_f32_16x16x32_bf16 v[60:63], v[80:83], v[60:63], v[88:91]
